# decode-first workgroups: bx >= 160 (96 workgroups) instead of bx >= 128
# baseline (speedup 1.0000x reference)
; DEV int lane_id() { int l; asm volatile("v_mbcnt_lo_u32_b32 %0, -1, 0\n\tv_mbcnt_hi_u32_b32 %0, -1, %0" : "=v"(l)); return l; }
; #define LAS __attribute__((address_space(3)))
; __global__ void __launch_bounds__(512, 2) mk_fwd(MKArgs args) {
;     ...
;         if (IN(pb + 2)) { LAYER_PTRS
;             { volatile LAS unsigned* LQ = (volatile LAS unsigned*)(ldsl + LDSCTL_OFF + 512);
;               unsigned* qd = (unsigned*)(ws + WS_CTL) + CW_Q3 + 128 * l; unsigned* qa = qd + 64;
;               const bool dclass = (bx >> 3) == 19 || (bx >> 3) == 27;
;               constexpr unsigned ND = SB * NSPLIT, NA = NB * MH * 8 + M / 256;
;               for (;;) {
;                   if (wave_s == 0 && lane_id() == 0) { unsigned kind = 2u, idx = 0u;
;                       if (dclass) { idx = __hip_atomic_fetch_add(qd, 1u, __ATOMIC_RELAXED, __HIP_MEMORY_SCOPE_AGENT); if (idx < ND) kind = 0u; else { idx = __hip_atomic_fetch_add(qa, 1u, __ATOMIC_RELAXED, __HIP_MEMORY_SCOPE_AGENT); if (idx < NA) kind = 1u; } }
;                       else { idx = __hip_atomic_fetch_add(qa, 1u, __ATOMIC_RELAXED, __HIP_MEMORY_SCOPE_AGENT); if (idx < NA) kind = 1u; else { idx = __hip_atomic_fetch_add(qd, 1u, __ATOMIC_RELAXED, __HIP_MEMORY_SCOPE_AGENT); if (idx < ND) kind = 0u; } }
;                       LQ[0] = kind; LQ[1] = idx; }
.LBB0_1240:
	s_waitcnt lgkmcnt(0)
	v_readlane_b32 s10, v255, 0
	v_readlane_b32 s14, v254, 1
	s_lshl_b32 s4, s10, 11
	v_readlane_b32 s15, v254, 2
	v_readlane_b32 s11, v255, 1
	s_barrier
	v_writelane_b32 v255, s4, 31
	v_readlane_b32 s4, v254, 9
	s_lshl_b32 s6, s10, 12
	s_load_dwordx2 s[22:23], s[14:15], 0x120
	v_readlane_b32 s5, v254, 10
	v_writelane_b32 v255, s6, 33
	s_load_dword s4, s[4:5], 0x0
	v_readlane_b32 s5, v254, 0
	v_writelane_b32 v255, s7, 34
	s_mov_b32 s6, s57
	s_waitcnt lgkmcnt(0)
	s_lshl_b64 s[0:1], s[10:11], 14
	s_lshl_b64 s[2:3], s[10:11], 20
	s_add_i32 s50, s6, 0
	v_readlane_b32 s4, v254, 52
	s_add_u32 s4, s22, s4
	s_addc_u32 s6, s23, 0
	s_add_i32 s51, s50, 0x20200
	s_lshl_b64 s[8:9], s[38:39], 2
	s_add_u32 s7, s22, s8
	v_writelane_b32 v255, s8, 40
	s_mul_hi_u32 s26, s10, 0x1400
	s_mul_i32 s27, s10, 0x1400
	v_writelane_b32 v255, s9, 41
	s_addc_u32 s8, s23, s9
	s_add_u32 s12, s7, 0xa6040
	s_addc_u32 s13, s8, 0
	v_writelane_b32 v255, s12, 26
	s_nop 1
	v_writelane_b32 v255, s13, 27
	s_add_u32 s12, s7, 0xa6140
	s_addc_u32 s13, s8, 0
	s_nop 0
	s_cmpk_lt_u32 s5, 0xa0
	s_cselect_b64 s[8:9], -1, 0
	s_add_i32 s52, s50, 0x20204
	s_add_i32 s53, s50, 0x17a00
	s_add_i32 s62, s50, 0x19e00
	s_add_u32 s63, s22, 0x1a798300
	s_addc_u32 s72, s23, 0
	s_add_i32 s73, s50, 0x15000
	s_add_i32 s78, s50, 0x1a000
	s_add_i32 s5, s50, 0x18e00
	s_add_u32 s2, s22, s2
	s_addc_u32 s3, s23, s3
	s_add_u32 s88, s2, 0x1a7d5300
	s_addc_u32 s89, s3, 0
	s_add_u32 s0, s22, s0
	s_addc_u32 s1, s23, s1
	s_add_u32 s40, s0, 0x1abd5300
	s_addc_u32 s41, s1, 0
	v_writelane_b32 v254, s5, 50
	s_add_u32 s0, s22, 0x9c400
	v_writelane_b32 v254, s0, 62
	s_addc_u32 s0, s23, 0
	v_writelane_b32 v254, s0, 60
	s_add_u32 s0, s22, 0x1a7c0300
	s_addc_u32 s37, s23, 0
	v_writelane_b32 v254, s0, 54
	s_add_u32 s0, s22, 0x1a7c5500
	v_writelane_b32 v254, s0, 58
	v_writelane_b32 v255, s12, 29
	v_readlane_b32 s0, v254, 47
	v_readlane_b32 s1, v254, 48
	v_writelane_b32 v255, s13, 30
	v_writelane_b32 v255, s8, 6
	s_addc_u32 s36, s23, 0
	s_lshl_b64 s[2:3], s[0:1], 2
	v_writelane_b32 v255, s9, 7
	s_add_u32 s0, s22, s2
	v_writelane_b32 v255, s2, 42
	s_addc_u32 s1, s23, s3
	s_add_u32 s0, s0, 0xce800
	v_writelane_b32 v255, s3, 43
	s_addc_u32 s1, s1, 0
	v_writelane_b32 v255, s0, 44
	s_nop 1
	v_writelane_b32 v255, s1, 45
	s_add_u32 s0, s22, 0xee58100
	v_writelane_b32 v255, s0, 10
	s_addc_u32 s0, s23, 0
	v_writelane_b32 v255, s0, 12
	s_add_u32 s0, s22, 0xfe58100
	v_writelane_b32 v254, s0, 49
	s_addc_u32 s0, s23, 0
	v_writelane_b32 v255, s0, 8
	s_add_u32 s0, s22, 0x10658100
	v_writelane_b32 v255, s0, 32
	s_addc_u32 s0, s23, 0
	v_writelane_b32 v255, s0, 18
	s_add_u32 s0, s22, 0x11658100
	v_writelane_b32 v255, s0, 20
	s_addc_u32 s0, s23, 0
	v_writelane_b32 v255, s0, 22
	s_add_u32 s0, s22, 0x11758100
	v_writelane_b32 v255, s0, 24
	s_addc_u32 s0, s23, 0
	v_writelane_b32 v255, s0, 28
	s_add_u32 s0, s22, 0xbc800
	v_writelane_b32 v255, s0, 14
	s_addc_u32 s0, s23, 0
	s_add_u32 s60, s22, 0x12758100
	s_addc_u32 s61, s23, 0
	s_add_u32 s64, s4, 0x4e0000
	s_addc_u32 s65, s6, 0
	s_add_u32 s42, s22, 0x12f58100
	s_addc_u32 s43, s23, 0
	s_add_i32 s38, s50, 0x10000
	v_writelane_b32 v255, s0, 46
	s_add_u32 s0, s4, 0x4f0000
	s_addc_u32 s1, s6, 0
	s_add_i32 s39, s50, 0x14000
	s_add_u32 s20, s4, 0x4e0080
	s_addc_u32 s21, s6, 0
	s_add_i32 s24, s50, 0x18000
	s_add_u32 s70, s4, 0x4f0080
	s_addc_u32 s71, s6, 0
	s_add_i32 s25, s50, 0x1c000
	s_add_u32 s80, s4, 0x4e0100
	s_addc_u32 s81, s6, 0
	s_add_u32 s2, s4, 0x4f0100
	s_addc_u32 s3, s6, 0
	s_add_u32 s58, s4, 0x4e0180
	s_addc_u32 s59, s6, 0
	s_add_u32 s54, s4, 0x4f0180
	s_addc_u32 s55, s6, 0
	s_branch .LBB0_1246
